# s10 + p6_wt: P6 output stores written through (sc1) so the 64 MB output drains during the epilogue, not at the end-of-kernel L2 write-back
# baseline (speedup 1.0000x reference)
.LBB0_678:
	ds_read_b128 v[144:147], v193
	ds_read_b128 v[148:151], v193 offset:1024
	ds_read_b128 v[152:155], v193 offset:2048
	ds_read_b128 v[156:159], v193 offset:3072
	ds_read_b128 v[160:163], v194
	ds_read_b128 v[164:167], v194 offset:1024
	ds_read_b128 v[168:171], v194 offset:2048
	ds_read_b128 v[172:175], v194 offset:3072
	s_cmp_eq_u32 s22, 0x7e04000
	s_cselect_b64 s[24:25], -1, 0
	s_and_b64 s[24:25], s[24:25], exec
	s_cselect_b32 s25, s9, s43
	s_cselect_b32 s24, s11, s42
	s_add_i32 s45, s44, 2
	s_cmp_eq_u32 s22, 0x7e04000
	s_cselect_b64 s[26:27], -1, 0
	s_and_b64 s[46:47], s[26:27], exec
	s_cselect_b32 s6, 0, s45
	s_and_b64 s[26:27], s[26:27], s[4:5]
	s_and_b64 s[26:27], s[26:27], exec
	s_cselect_b32 s26, s15, s21
	s_cselect_b32 s27, s14, s20
	v_lshl_add_u64 v[188:189], v[140:141], 0, s[22:23]
	s_add_i32 m0, s19, 0xc000
	ds_read_b128 v[176:179], v195
	ds_read_b128 v[180:183], v195 offset:1024
	ds_read_b128 v[184:187], v195 offset:2048
	ds_read_b128 v[196:199], v195 offset:3072
	ds_read_b128 v[200:203], v195 offset:4096
	ds_read_b128 v[204:207], v195 offset:5120
	ds_read_b128 v[208:211], v195 offset:6144
	ds_read_b128 v[212:215], v195 offset:7168
	global_load_lds_dwordx4 v[188:189], off
	v_lshl_add_u64 v[188:189], v[142:143], 0, s[22:23]
	s_add_i32 m0, s19, 0xe000
	s_nop 0
	global_load_lds_dwordx4 v[188:189], off
	s_waitcnt vmcnt(8)
	s_waitcnt lgkmcnt(0)
	s_barrier
	s_setprio 1
	v_mfma_f32_16x16x32_bf16 v[124:127], v[144:147], v[176:179], v[124:127]
	v_mfma_f32_16x16x32_bf16 v[120:123], v[152:155], v[176:179], v[120:123]
	v_mfma_f32_16x16x32_bf16 v[112:115], v[144:147], v[184:187], v[112:115]
	v_mfma_f32_16x16x32_bf16 v[104:107], v[152:155], v[184:187], v[104:107]
	v_mfma_f32_16x16x32_bf16 v[96:99], v[144:147], v[200:203], v[96:99]
	v_mfma_f32_16x16x32_bf16 v[88:91], v[152:155], v[200:203], v[88:91]
	v_mfma_f32_16x16x32_bf16 v[80:83], v[144:147], v[208:211], v[80:83]
	v_mfma_f32_16x16x32_bf16 v[72:75], v[152:155], v[208:211], v[72:75]
	v_mfma_f32_16x16x32_bf16 v[124:127], v[148:151], v[180:183], v[124:127]
	v_mfma_f32_16x16x32_bf16 v[120:123], v[156:159], v[180:183], v[120:123]
	v_mfma_f32_16x16x32_bf16 v[112:115], v[148:151], v[196:199], v[112:115]
	v_mfma_f32_16x16x32_bf16 v[104:107], v[156:159], v[196:199], v[104:107]
	v_mfma_f32_16x16x32_bf16 v[96:99], v[148:151], v[204:207], v[96:99]
	v_mfma_f32_16x16x32_bf16 v[88:91], v[156:159], v[204:207], v[88:91]
	v_mfma_f32_16x16x32_bf16 v[80:83], v[148:151], v[212:215], v[80:83]
	v_mfma_f32_16x16x32_bf16 v[72:75], v[156:159], v[212:215], v[72:75]
	s_setprio 0
	s_setprio 1
	v_mfma_f32_16x16x32_bf16 v[116:119], v[160:163], v[176:179], v[116:119]
	v_mfma_f32_16x16x32_bf16 v[108:111], v[168:171], v[176:179], v[108:111]
	v_mfma_f32_16x16x32_bf16 v[100:103], v[160:163], v[184:187], v[100:103]
	v_mfma_f32_16x16x32_bf16 v[92:95], v[168:171], v[184:187], v[92:95]
	v_mfma_f32_16x16x32_bf16 v[84:87], v[160:163], v[200:203], v[84:87]
	v_mfma_f32_16x16x32_bf16 v[76:79], v[168:171], v[200:203], v[76:79]
	v_mfma_f32_16x16x32_bf16 v[68:71], v[160:163], v[208:211], v[68:71]
	v_mfma_f32_16x16x32_bf16 v[64:67], v[168:171], v[208:211], v[64:67]
	v_mfma_f32_16x16x32_bf16 v[116:119], v[164:167], v[180:183], v[116:119]
	v_mfma_f32_16x16x32_bf16 v[108:111], v[172:175], v[180:183], v[108:111]
	v_mfma_f32_16x16x32_bf16 v[100:103], v[164:167], v[196:199], v[100:103]
	v_mfma_f32_16x16x32_bf16 v[92:95], v[172:175], v[196:199], v[92:95]
	v_mfma_f32_16x16x32_bf16 v[84:87], v[164:167], v[204:207], v[84:87]
	v_mfma_f32_16x16x32_bf16 v[76:79], v[172:175], v[204:207], v[76:79]
	v_mfma_f32_16x16x32_bf16 v[68:71], v[164:167], v[212:215], v[68:71]
	v_mfma_f32_16x16x32_bf16 v[64:67], v[172:175], v[212:215], v[64:67]
	s_setprio 0
	s_barrier
	s_add_i32 s46, s38, s29
	v_lshl_add_u64 v[188:189], s[24:25], 0, v[128:129]
	s_mov_b32 m0, s46
	ds_read_b128 v[176:179], v195 offset:16384
	ds_read_b128 v[180:183], v195 offset:17408
	ds_read_b128 v[184:187], v195 offset:18432
	ds_read_b128 v[196:199], v195 offset:19456
	ds_read_b128 v[200:203], v195 offset:20480
	ds_read_b128 v[204:207], v195 offset:21504
	ds_read_b128 v[208:211], v195 offset:22528
	ds_read_b128 v[212:215], v195 offset:23552
	global_load_lds_dwordx4 v[188:189], off
	s_add_i32 m0, s46, 0x2000
	s_add_u32 s46, s24, 0x4000
	v_lshl_add_u64 v[188:189], s[24:25], 0, v[130:131]
	s_addc_u32 s47, s25, 0
	s_add_i32 s48, s39, s29
	global_load_lds_dwordx4 v[188:189], off
	v_lshl_add_u64 v[188:189], s[46:47], 0, v[128:129]
	s_mov_b32 m0, s48
	s_nop 0
	global_load_lds_dwordx4 v[188:189], off
	v_lshl_add_u64 v[188:189], s[46:47], 0, v[130:131]
	s_add_i32 m0, s48, 0x2000
	s_lshl_b64 s[46:47], s[6:7], 21
	s_add_u32 s46, s27, s46
	s_addc_u32 s47, s26, s47
	global_load_lds_dwordx4 v[188:189], off
	v_lshl_add_u64 v[188:189], s[46:47], 0, v[128:129]
	s_mov_b32 m0, s19
	s_nop 0
	global_load_lds_dwordx4 v[188:189], off
	v_lshl_add_u64 v[188:189], s[46:47], 0, v[130:131]
	s_mov_b32 m0, s31
	s_nop 0
	global_load_lds_dwordx4 v[188:189], off
	s_waitcnt vmcnt(8)
	s_waitcnt lgkmcnt(0)
	s_barrier
	s_setprio 1
	v_mfma_f32_16x16x32_bf16 v[60:63], v[144:147], v[176:179], v[60:63]
	v_mfma_f32_16x16x32_bf16 v[56:59], v[152:155], v[176:179], v[56:59]
	v_mfma_f32_16x16x32_bf16 v[48:51], v[144:147], v[184:187], v[48:51]
	v_mfma_f32_16x16x32_bf16 v[40:43], v[152:155], v[184:187], v[40:43]
	v_mfma_f32_16x16x32_bf16 v[32:35], v[144:147], v[200:203], v[32:35]
	v_mfma_f32_16x16x32_bf16 v[24:27], v[152:155], v[200:203], v[24:27]
	v_mfma_f32_16x16x32_bf16 v[16:19], v[144:147], v[208:211], v[16:19]
	v_mfma_f32_16x16x32_bf16 v[8:11], v[152:155], v[208:211], v[8:11]
	v_mfma_f32_16x16x32_bf16 v[60:63], v[148:151], v[180:183], v[60:63]
	v_mfma_f32_16x16x32_bf16 v[56:59], v[156:159], v[180:183], v[56:59]
	v_mfma_f32_16x16x32_bf16 v[48:51], v[148:151], v[196:199], v[48:51]
	v_mfma_f32_16x16x32_bf16 v[40:43], v[156:159], v[196:199], v[40:43]
	v_mfma_f32_16x16x32_bf16 v[32:35], v[148:151], v[204:207], v[32:35]
	v_mfma_f32_16x16x32_bf16 v[24:27], v[156:159], v[204:207], v[24:27]
	v_mfma_f32_16x16x32_bf16 v[16:19], v[148:151], v[212:215], v[16:19]
	v_mfma_f32_16x16x32_bf16 v[8:11], v[156:159], v[212:215], v[8:11]
	s_setprio 0
	s_setprio 1
	v_mfma_f32_16x16x32_bf16 v[52:55], v[160:163], v[176:179], v[52:55]
	v_mfma_f32_16x16x32_bf16 v[44:47], v[168:171], v[176:179], v[44:47]
	v_mfma_f32_16x16x32_bf16 v[36:39], v[160:163], v[184:187], v[36:39]
	v_mfma_f32_16x16x32_bf16 v[28:31], v[168:171], v[184:187], v[28:31]
	v_mfma_f32_16x16x32_bf16 v[20:23], v[160:163], v[200:203], v[20:23]
	v_mfma_f32_16x16x32_bf16 v[12:15], v[168:171], v[200:203], v[12:15]
	v_mfma_f32_16x16x32_bf16 v[4:7], v[160:163], v[208:211], v[4:7]
	v_mfma_f32_16x16x32_bf16 v[0:3], v[168:171], v[208:211], v[0:3]
	v_mfma_f32_16x16x32_bf16 v[52:55], v[164:167], v[180:183], v[52:55]
	v_mfma_f32_16x16x32_bf16 v[44:47], v[172:175], v[180:183], v[44:47]
	v_mfma_f32_16x16x32_bf16 v[36:39], v[164:167], v[196:199], v[36:39]
	v_mfma_f32_16x16x32_bf16 v[28:31], v[172:175], v[196:199], v[28:31]
	v_mfma_f32_16x16x32_bf16 v[20:23], v[164:167], v[204:207], v[20:23]
	v_mfma_f32_16x16x32_bf16 v[12:15], v[172:175], v[204:207], v[12:15]
	v_mfma_f32_16x16x32_bf16 v[4:7], v[164:167], v[212:215], v[4:7]
	v_mfma_f32_16x16x32_bf16 v[0:3], v[172:175], v[212:215], v[0:3]
	s_setprio 0
	s_barrier
	s_add_i32 s48, 0, 0x18000
	s_add_i32 s49, 0, 0x1c000
	v_add_u32_e32 v156, s48, v191
	v_add_u32_e32 v172, s49, v191
	ds_read_b128 v[144:147], v156
	ds_read_b128 v[148:151], v156 offset:1024
	ds_read_b128 v[152:155], v156 offset:2048
	ds_read_b128 v[156:159], v156 offset:3072
	ds_read_b128 v[160:163], v172
	ds_read_b128 v[164:167], v172 offset:1024
	ds_read_b128 v[168:171], v172 offset:2048
	ds_read_b128 v[172:175], v172 offset:3072
	s_add_u32 s46, s46, 0x4000
	s_addc_u32 s47, s47, 0
	s_mov_b32 m0, s33
	v_lshl_add_u64 v[188:189], s[46:47], 0, v[128:129]
	ds_read_b128 v[176:179], v195 offset:32768
	ds_read_b128 v[180:183], v195 offset:33792
	ds_read_b128 v[184:187], v195 offset:34816
	ds_read_b128 v[196:199], v195 offset:35840
	ds_read_b128 v[200:203], v195 offset:36864
	ds_read_b128 v[204:207], v195 offset:37888
	ds_read_b128 v[208:211], v195 offset:38912
	ds_read_b128 v[212:215], v195 offset:39936
	global_load_lds_dwordx4 v[188:189], off
	v_lshl_add_u64 v[188:189], s[46:47], 0, v[130:131]
	s_mov_b32 m0, s34
	s_nop 0
	global_load_lds_dwordx4 v[188:189], off
	s_waitcnt vmcnt(8)
	s_waitcnt lgkmcnt(0)
	s_barrier
	s_setprio 1
	v_mfma_f32_16x16x32_bf16 v[124:127], v[144:147], v[176:179], v[124:127]
	v_mfma_f32_16x16x32_bf16 v[120:123], v[152:155], v[176:179], v[120:123]
	v_mfma_f32_16x16x32_bf16 v[112:115], v[144:147], v[184:187], v[112:115]
	v_mfma_f32_16x16x32_bf16 v[104:107], v[152:155], v[184:187], v[104:107]
	v_mfma_f32_16x16x32_bf16 v[96:99], v[144:147], v[200:203], v[96:99]
	v_mfma_f32_16x16x32_bf16 v[88:91], v[152:155], v[200:203], v[88:91]
	v_mfma_f32_16x16x32_bf16 v[80:83], v[144:147], v[208:211], v[80:83]
	v_mfma_f32_16x16x32_bf16 v[72:75], v[152:155], v[208:211], v[72:75]
	v_mfma_f32_16x16x32_bf16 v[124:127], v[148:151], v[180:183], v[124:127]
	v_mfma_f32_16x16x32_bf16 v[120:123], v[156:159], v[180:183], v[120:123]
	v_mfma_f32_16x16x32_bf16 v[112:115], v[148:151], v[196:199], v[112:115]
	v_mfma_f32_16x16x32_bf16 v[104:107], v[156:159], v[196:199], v[104:107]
	v_mfma_f32_16x16x32_bf16 v[96:99], v[148:151], v[204:207], v[96:99]
	v_mfma_f32_16x16x32_bf16 v[88:91], v[156:159], v[204:207], v[88:91]
	v_mfma_f32_16x16x32_bf16 v[80:83], v[148:151], v[212:215], v[80:83]
	v_mfma_f32_16x16x32_bf16 v[72:75], v[156:159], v[212:215], v[72:75]
	s_setprio 0
	s_setprio 1
	v_mfma_f32_16x16x32_bf16 v[116:119], v[160:163], v[176:179], v[116:119]
	v_mfma_f32_16x16x32_bf16 v[108:111], v[168:171], v[176:179], v[108:111]
	v_mfma_f32_16x16x32_bf16 v[100:103], v[160:163], v[184:187], v[100:103]
	v_mfma_f32_16x16x32_bf16 v[92:95], v[168:171], v[184:187], v[92:95]
	v_mfma_f32_16x16x32_bf16 v[84:87], v[160:163], v[200:203], v[84:87]
	v_mfma_f32_16x16x32_bf16 v[76:79], v[168:171], v[200:203], v[76:79]
	v_mfma_f32_16x16x32_bf16 v[68:71], v[160:163], v[208:211], v[68:71]
	v_mfma_f32_16x16x32_bf16 v[64:67], v[168:171], v[208:211], v[64:67]
	v_mfma_f32_16x16x32_bf16 v[116:119], v[164:167], v[180:183], v[116:119]
	v_mfma_f32_16x16x32_bf16 v[108:111], v[172:175], v[180:183], v[108:111]
	v_mfma_f32_16x16x32_bf16 v[100:103], v[164:167], v[196:199], v[100:103]
	v_mfma_f32_16x16x32_bf16 v[92:95], v[172:175], v[196:199], v[92:95]
	v_mfma_f32_16x16x32_bf16 v[84:87], v[164:167], v[204:207], v[84:87]
	v_mfma_f32_16x16x32_bf16 v[76:79], v[172:175], v[204:207], v[76:79]
	v_mfma_f32_16x16x32_bf16 v[68:71], v[164:167], v[212:215], v[68:71]
	v_mfma_f32_16x16x32_bf16 v[64:67], v[172:175], v[212:215], v[64:67]
	s_setprio 0
	s_barrier
	s_add_u32 s46, s24, 0x20000
	s_addc_u32 s47, s25, 0
	s_add_i32 s48, s48, s29
	v_lshl_add_u64 v[188:189], s[46:47], 0, v[128:129]
	s_mov_b32 m0, s48
	ds_read_b128 v[176:179], v195 offset:49152
	ds_read_b128 v[180:183], v195 offset:50176
	ds_read_b128 v[184:187], v195 offset:51200
	ds_read_b128 v[196:199], v195 offset:52224
	ds_read_b128 v[200:203], v195 offset:53248
	ds_read_b128 v[204:207], v195 offset:54272
	ds_read_b128 v[208:211], v195 offset:55296
	ds_read_b128 v[212:215], v195 offset:56320
	global_load_lds_dwordx4 v[188:189], off
	s_add_i32 m0, s48, 0x2000
	s_add_u32 s24, s24, 0x24000
	v_lshl_add_u64 v[188:189], s[46:47], 0, v[130:131]
	s_addc_u32 s25, s25, 0
	s_add_i32 s46, s49, s29
	global_load_lds_dwordx4 v[188:189], off
	v_lshl_add_u64 v[188:189], s[24:25], 0, v[128:129]
	s_mov_b32 m0, s46
	s_or_b32 s6, s6, 1
	global_load_lds_dwordx4 v[188:189], off
	v_lshl_add_u64 v[188:189], s[24:25], 0, v[130:131]
	s_add_i32 m0, s46, 0x2000
	s_lshl_b64 s[24:25], s[6:7], 21
	s_add_u32 s24, s27, s24
	s_addc_u32 s25, s26, s25
	global_load_lds_dwordx4 v[188:189], off
	v_lshl_add_u64 v[188:189], s[24:25], 0, v[128:129]
	s_mov_b32 m0, s36
	s_nop 0
	global_load_lds_dwordx4 v[188:189], off
	v_lshl_add_u64 v[188:189], s[24:25], 0, v[130:131]
	s_mov_b32 m0, s37
	s_nop 0
	global_load_lds_dwordx4 v[188:189], off
	s_waitcnt vmcnt(8)
	s_waitcnt lgkmcnt(0)
	s_barrier
	s_setprio 1
	v_mfma_f32_16x16x32_bf16 v[60:63], v[144:147], v[176:179], v[60:63]
	v_mfma_f32_16x16x32_bf16 v[56:59], v[152:155], v[176:179], v[56:59]
	v_mfma_f32_16x16x32_bf16 v[48:51], v[144:147], v[184:187], v[48:51]
	v_mfma_f32_16x16x32_bf16 v[40:43], v[152:155], v[184:187], v[40:43]
	v_mfma_f32_16x16x32_bf16 v[32:35], v[144:147], v[200:203], v[32:35]
	v_mfma_f32_16x16x32_bf16 v[24:27], v[152:155], v[200:203], v[24:27]
	v_mfma_f32_16x16x32_bf16 v[16:19], v[144:147], v[208:211], v[16:19]
	v_mfma_f32_16x16x32_bf16 v[8:11], v[152:155], v[208:211], v[8:11]
	v_mfma_f32_16x16x32_bf16 v[60:63], v[148:151], v[180:183], v[60:63]
	v_mfma_f32_16x16x32_bf16 v[56:59], v[156:159], v[180:183], v[56:59]
	v_mfma_f32_16x16x32_bf16 v[48:51], v[148:151], v[196:199], v[48:51]
	v_mfma_f32_16x16x32_bf16 v[40:43], v[156:159], v[196:199], v[40:43]
	v_mfma_f32_16x16x32_bf16 v[32:35], v[148:151], v[204:207], v[32:35]
	v_mfma_f32_16x16x32_bf16 v[24:27], v[156:159], v[204:207], v[24:27]
	v_mfma_f32_16x16x32_bf16 v[16:19], v[148:151], v[212:215], v[16:19]
	v_mfma_f32_16x16x32_bf16 v[8:11], v[156:159], v[212:215], v[8:11]
	s_setprio 0
	s_setprio 1
	v_mfma_f32_16x16x32_bf16 v[52:55], v[160:163], v[176:179], v[52:55]
	v_mfma_f32_16x16x32_bf16 v[44:47], v[168:171], v[176:179], v[44:47]
	v_mfma_f32_16x16x32_bf16 v[36:39], v[160:163], v[184:187], v[36:39]
	v_mfma_f32_16x16x32_bf16 v[28:31], v[168:171], v[184:187], v[28:31]
	v_mfma_f32_16x16x32_bf16 v[20:23], v[160:163], v[200:203], v[20:23]
	v_mfma_f32_16x16x32_bf16 v[12:15], v[168:171], v[200:203], v[12:15]
	v_mfma_f32_16x16x32_bf16 v[4:7], v[160:163], v[208:211], v[4:7]
	v_mfma_f32_16x16x32_bf16 v[0:3], v[168:171], v[208:211], v[0:3]
	v_mfma_f32_16x16x32_bf16 v[52:55], v[164:167], v[180:183], v[52:55]
	v_mfma_f32_16x16x32_bf16 v[44:47], v[172:175], v[180:183], v[44:47]
	v_mfma_f32_16x16x32_bf16 v[36:39], v[164:167], v[196:199], v[36:39]
	v_mfma_f32_16x16x32_bf16 v[28:31], v[172:175], v[196:199], v[28:31]
	v_mfma_f32_16x16x32_bf16 v[20:23], v[164:167], v[204:207], v[20:23]
	v_mfma_f32_16x16x32_bf16 v[12:15], v[172:175], v[204:207], v[12:15]
	v_mfma_f32_16x16x32_bf16 v[4:7], v[164:167], v[212:215], v[4:7]
	v_mfma_f32_16x16x32_bf16 v[0:3], v[172:175], v[212:215], v[0:3]
	s_setprio 0
	s_barrier
	s_add_u32 s22, s22, 0x400000
	s_addc_u32 s23, s23, 0
	s_add_u32 s42, s42, 0x40000
	s_addc_u32 s43, s43, 0
	s_cmp_gt_u32 s44, 61
	s_mov_b32 s44, s45
	s_cbranch_scc0 .LBB0_678
	v_lshl_or_b32 v142, s41, 8, v192
	v_lshl_add_u32 v144, s18, 8, v190
	v_ashrrev_i32_e32 v143, 31, v142
	v_ashrrev_i32_e32 v145, 31, v144
	v_lshl_add_u64 v[146:147], v[142:143], 1, s[12:13]
	v_lshlrev_b64 v[140:141], 11, v[144:145]
	v_lshl_add_u64 v[140:141], v[146:147], 0, v[140:141]
	global_load_dwordx2 v[196:197], v[140:141], off
	global_load_dwordx2 v[198:199], v[140:141], off offset:32
	global_load_dwordx2 v[200:201], v[140:141], off offset:256
	v_or_b32_e32 v202, 16, v144
	v_ashrrev_i32_e32 v203, 31, v202
	global_load_dwordx2 v[204:205], v[140:141], off offset:288
	v_lshlrev_b64 v[140:141], 11, v[202:203]
	v_lshl_add_u64 v[148:149], v[146:147], 0, v[140:141]
	global_load_dwordx2 v[206:207], v[148:149], off
	global_load_dwordx2 v[208:209], v[148:149], off offset:32
	global_load_dwordx2 v[210:211], v[148:149], off offset:256
	global_load_dwordx2 v[212:213], v[148:149], off offset:288
	v_or_b32_e32 v188, 32, v144
	v_or_b32_e32 v178, 48, v144
	v_add_u32_e32 v168, 0x80, v144
	v_add_u32_e32 v160, 0x90, v144
	v_add_u32_e32 v150, 0xa0, v144
	v_add_u32_e32 v140, 0xb0, v144
	v_ashrrev_i32_e32 v189, 31, v188
	v_ashrrev_i32_e32 v179, 31, v178
	v_ashrrev_i32_e32 v169, 31, v168
	v_ashrrev_i32_e32 v161, 31, v160
	v_ashrrev_i32_e32 v151, 31, v150
	v_ashrrev_i32_e32 v141, 31, v140
	v_lshlrev_b64 v[152:153], 12, v[144:145]
	v_lshlrev_b64 v[144:145], 2, v[142:143]
	v_lshlrev_b64 v[142:143], 11, v[188:189]
	v_lshlrev_b64 v[154:155], 11, v[178:179]
	v_lshlrev_b64 v[156:157], 11, v[168:169]
	v_lshlrev_b64 v[158:159], 11, v[160:161]
	v_lshlrev_b64 v[162:163], 11, v[150:151]
	v_lshlrev_b64 v[164:165], 11, v[140:141]
	v_lshl_add_u64 v[152:153], s[78:79], 0, v[152:153]
	v_lshl_add_u64 v[142:143], v[146:147], 0, v[142:143]
	v_lshl_add_u64 v[154:155], v[146:147], 0, v[154:155]
	v_lshl_add_u64 v[156:157], v[146:147], 0, v[156:157]
	v_lshl_add_u64 v[158:159], v[146:147], 0, v[158:159]
	v_lshl_add_u64 v[148:149], v[146:147], 0, v[162:163]
	v_lshl_add_u64 v[214:215], v[146:147], 0, v[164:165]
	v_lshl_add_u64 v[216:217], v[152:153], 0, v[144:145]
	global_load_dwordx2 v[218:219], v[142:143], off
	global_load_dwordx2 v[220:221], v[142:143], off offset:32
	global_load_dwordx2 v[222:223], v[142:143], off offset:256
	global_load_dwordx2 v[224:225], v[142:143], off offset:288
	global_load_dwordx2 v[226:227], v[154:155], off
	global_load_dwordx2 v[228:229], v[154:155], off offset:32
	global_load_dwordx2 v[186:187], v[154:155], off offset:256
	global_load_dwordx2 v[184:185], v[154:155], off offset:288
	global_load_dwordx2 v[182:183], v[156:157], off
	global_load_dwordx2 v[180:181], v[156:157], off offset:32
	global_load_dwordx2 v[176:177], v[156:157], off offset:256
	global_load_dwordx2 v[174:175], v[156:157], off offset:288
	global_load_dwordx2 v[172:173], v[158:159], off
	global_load_dwordx2 v[170:171], v[158:159], off offset:32
	global_load_dwordx2 v[166:167], v[158:159], off offset:256
	global_load_dwordx2 v[164:165], v[158:159], off offset:288
	global_load_dwordx2 v[162:163], v[148:149], off
	s_nop 0
	global_load_dwordx2 v[158:159], v[148:149], off offset:32
	global_load_dwordx2 v[156:157], v[148:149], off offset:256
	global_load_dwordx2 v[154:155], v[148:149], off offset:288
	global_load_dwordx2 v[152:153], v[214:215], off
	s_nop 0
	global_load_dwordx2 v[148:149], v[214:215], off offset:32
	global_load_dwordx2 v[146:147], v[214:215], off offset:256
	global_load_dwordx2 v[142:143], v[214:215], off offset:288
	s_and_b64 vcc, exec, s[0:1]
	s_mov_b32 s41, s8
	s_mov_b32 s18, s10
	s_mov_b64 s[22:23], s[16:17]
	s_mov_b64 s[20:21], s[14:15]
	s_waitcnt vmcnt(0)
	v_lshlrev_b32_e32 v214, 16, v196
	v_and_b32_e32 v215, 0xffff0000, v196
	v_lshlrev_b32_e32 v196, 16, v197
	v_and_b32_e32 v197, 0xffff0000, v197
	v_lshlrev_b32_e32 v230, 16, v198
	v_and_b32_e32 v231, 0xffff0000, v198
	v_lshlrev_b32_e32 v198, 16, v199
	v_and_b32_e32 v199, 0xffff0000, v199
	v_pk_add_f32 v[126:127], v[126:127], v[196:197]
	v_pk_add_f32 v[124:125], v[124:125], v[214:215]
	v_pk_add_f32 v[120:121], v[120:121], v[230:231]
	v_lshlrev_b32_e32 v232, 16, v200
	v_and_b32_e32 v233, 0xffff0000, v200
	v_pk_add_f32 v[122:123], v[122:123], v[198:199]
	global_store_dwordx4 v[216:217], v[124:127], off sc1
	global_store_dwordx4 v[216:217], v[120:123], off offset:64 sc1
	v_pk_add_f32 v[116:117], v[116:117], v[232:233]
	s_nop 0
	v_lshlrev_b32_e32 v120, 16, v201
	v_and_b32_e32 v121, 0xffff0000, v201
	v_pk_add_f32 v[118:119], v[118:119], v[120:121]
	global_store_dwordx4 v[216:217], v[116:119], off offset:512 sc1
	s_nop 1
	v_lshlrev_b32_e32 v116, 16, v204
	v_and_b32_e32 v117, 0xffff0000, v204
	v_lshlrev_b32_e32 v118, 16, v205
	v_and_b32_e32 v119, 0xffff0000, v205
	v_pk_add_f32 v[110:111], v[110:111], v[118:119]
	v_pk_add_f32 v[108:109], v[108:109], v[116:117]
	global_store_dwordx4 v[216:217], v[108:111], off offset:576 sc1
	v_lshlrev_b64 v[116:117], 12, v[202:203]
	s_nop 0
	v_lshlrev_b32_e32 v108, 16, v206
	v_and_b32_e32 v109, 0xffff0000, v206
	v_lshlrev_b32_e32 v110, 16, v207
	v_and_b32_e32 v111, 0xffff0000, v207
	v_pk_add_f32 v[108:109], v[112:113], v[108:109]
	v_lshl_add_u64 v[112:113], s[78:79], 0, v[116:117]
	v_pk_add_f32 v[110:111], v[114:115], v[110:111]
	v_lshl_add_u64 v[112:113], v[112:113], 0, v[144:145]
	global_store_dwordx4 v[112:113], v[108:111], off sc1
	s_nop 1
	v_lshlrev_b32_e32 v108, 16, v208
	v_and_b32_e32 v109, 0xffff0000, v208
	v_lshlrev_b32_e32 v110, 16, v209
	v_and_b32_e32 v111, 0xffff0000, v209
	v_pk_add_f32 v[106:107], v[106:107], v[110:111]
	v_pk_add_f32 v[104:105], v[104:105], v[108:109]
	global_store_dwordx4 v[112:113], v[104:107], off offset:64 sc1
	s_nop 1
	v_lshlrev_b32_e32 v104, 16, v210
	v_and_b32_e32 v105, 0xffff0000, v210
	v_lshlrev_b32_e32 v106, 16, v211
	v_and_b32_e32 v107, 0xffff0000, v211
	v_pk_add_f32 v[102:103], v[102:103], v[106:107]
	v_pk_add_f32 v[100:101], v[100:101], v[104:105]
	global_store_dwordx4 v[112:113], v[100:103], off offset:512 sc1
	s_nop 1
	v_lshlrev_b32_e32 v100, 16, v212
	v_and_b32_e32 v101, 0xffff0000, v212
	v_lshlrev_b32_e32 v102, 16, v213
	v_and_b32_e32 v103, 0xffff0000, v213
	v_pk_add_f32 v[94:95], v[94:95], v[102:103]
	v_pk_add_f32 v[92:93], v[92:93], v[100:101]
	global_store_dwordx4 v[112:113], v[92:95], off offset:576 sc1
	v_lshlrev_b64 v[100:101], 12, v[188:189]
	s_nop 0
	v_lshlrev_b32_e32 v92, 16, v218
	v_and_b32_e32 v93, 0xffff0000, v218
	v_lshlrev_b32_e32 v94, 16, v219
	v_and_b32_e32 v95, 0xffff0000, v219
	v_pk_add_f32 v[92:93], v[96:97], v[92:93]
	v_lshl_add_u64 v[96:97], s[78:79], 0, v[100:101]
	v_pk_add_f32 v[94:95], v[98:99], v[94:95]
	v_lshl_add_u64 v[96:97], v[96:97], 0, v[144:145]
	global_store_dwordx4 v[96:97], v[92:95], off sc1
	s_nop 1
	v_lshlrev_b32_e32 v92, 16, v220
	v_and_b32_e32 v93, 0xffff0000, v220
	v_lshlrev_b32_e32 v94, 16, v221
	v_and_b32_e32 v95, 0xffff0000, v221
	v_pk_add_f32 v[90:91], v[90:91], v[94:95]
	v_pk_add_f32 v[88:89], v[88:89], v[92:93]
	global_store_dwordx4 v[96:97], v[88:91], off offset:64 sc1
	s_nop 1
	v_lshlrev_b32_e32 v88, 16, v222
	v_and_b32_e32 v89, 0xffff0000, v222
	v_lshlrev_b32_e32 v90, 16, v223
	v_and_b32_e32 v91, 0xffff0000, v223
	v_pk_add_f32 v[86:87], v[86:87], v[90:91]
	v_pk_add_f32 v[84:85], v[84:85], v[88:89]
	global_store_dwordx4 v[96:97], v[84:87], off offset:512 sc1
	s_nop 1
	v_lshlrev_b32_e32 v84, 16, v224
	v_and_b32_e32 v85, 0xffff0000, v224
	v_lshlrev_b32_e32 v86, 16, v225
	v_and_b32_e32 v87, 0xffff0000, v225
	v_pk_add_f32 v[78:79], v[78:79], v[86:87]
	v_pk_add_f32 v[76:77], v[76:77], v[84:85]
	global_store_dwordx4 v[96:97], v[76:79], off offset:576 sc1
	v_lshlrev_b64 v[84:85], 12, v[178:179]
	s_nop 0
	v_lshlrev_b32_e32 v76, 16, v226
	v_and_b32_e32 v77, 0xffff0000, v226
	v_lshlrev_b32_e32 v78, 16, v227
	v_and_b32_e32 v79, 0xffff0000, v227
	v_pk_add_f32 v[76:77], v[80:81], v[76:77]
	v_lshl_add_u64 v[80:81], s[78:79], 0, v[84:85]
	v_pk_add_f32 v[78:79], v[82:83], v[78:79]
	v_lshl_add_u64 v[80:81], v[80:81], 0, v[144:145]
	global_store_dwordx4 v[80:81], v[76:79], off sc1
	s_nop 1
	v_lshlrev_b32_e32 v76, 16, v228
	v_and_b32_e32 v77, 0xffff0000, v228
	v_lshlrev_b32_e32 v78, 16, v229
	v_and_b32_e32 v79, 0xffff0000, v229
	v_pk_add_f32 v[74:75], v[74:75], v[78:79]
	v_pk_add_f32 v[72:73], v[72:73], v[76:77]
	global_store_dwordx4 v[80:81], v[72:75], off offset:64 sc1
	s_nop 1
	v_lshlrev_b32_e32 v72, 16, v186
	v_and_b32_e32 v73, 0xffff0000, v186
	v_lshlrev_b32_e32 v74, 16, v187
	v_and_b32_e32 v75, 0xffff0000, v187
	v_pk_add_f32 v[70:71], v[70:71], v[74:75]
	v_pk_add_f32 v[68:69], v[68:69], v[72:73]
	global_store_dwordx4 v[80:81], v[68:71], off offset:512 sc1
	s_nop 1
	v_lshlrev_b32_e32 v68, 16, v184
	v_and_b32_e32 v69, 0xffff0000, v184
	v_lshlrev_b32_e32 v70, 16, v185
	v_and_b32_e32 v71, 0xffff0000, v185
	v_pk_add_f32 v[66:67], v[66:67], v[70:71]
	v_pk_add_f32 v[64:65], v[64:65], v[68:69]
	global_store_dwordx4 v[80:81], v[64:67], off offset:576 sc1
	v_lshlrev_b32_e32 v68, 16, v183
	v_and_b32_e32 v69, 0xffff0000, v183
	v_lshlrev_b64 v[64:65], 12, v[168:169]
	v_lshlrev_b32_e32 v66, 16, v182
	v_and_b32_e32 v67, 0xffff0000, v182
	v_lshl_add_u64 v[64:65], s[78:79], 0, v[64:65]
	v_pk_add_f32 v[62:63], v[62:63], v[68:69]
	v_pk_add_f32 v[60:61], v[60:61], v[66:67]
	v_lshl_add_u64 v[64:65], v[64:65], 0, v[144:145]
	global_store_dwordx4 v[64:65], v[60:63], off sc1
	s_nop 1
	v_lshlrev_b32_e32 v60, 16, v180
	v_and_b32_e32 v61, 0xffff0000, v180
	v_lshlrev_b32_e32 v62, 16, v181
	v_and_b32_e32 v63, 0xffff0000, v181
	v_pk_add_f32 v[58:59], v[58:59], v[62:63]
	v_pk_add_f32 v[56:57], v[56:57], v[60:61]
	global_store_dwordx4 v[64:65], v[56:59], off offset:64 sc1
	s_nop 1
	v_lshlrev_b32_e32 v56, 16, v176
	v_and_b32_e32 v57, 0xffff0000, v176
	v_lshlrev_b32_e32 v58, 16, v177
	v_and_b32_e32 v59, 0xffff0000, v177
	v_pk_add_f32 v[54:55], v[54:55], v[58:59]
	v_pk_add_f32 v[52:53], v[52:53], v[56:57]
	global_store_dwordx4 v[64:65], v[52:55], off offset:512 sc1
	s_nop 1
	v_lshlrev_b32_e32 v52, 16, v174
	v_and_b32_e32 v53, 0xffff0000, v174
	v_lshlrev_b32_e32 v54, 16, v175
	v_and_b32_e32 v55, 0xffff0000, v175
	v_pk_add_f32 v[46:47], v[46:47], v[54:55]
	v_pk_add_f32 v[44:45], v[44:45], v[52:53]
	global_store_dwordx4 v[64:65], v[44:47], off offset:576 sc1
	v_lshlrev_b64 v[52:53], 12, v[160:161]
	s_nop 0
	v_lshlrev_b32_e32 v44, 16, v172
	v_and_b32_e32 v45, 0xffff0000, v172
	v_lshlrev_b32_e32 v46, 16, v173
	v_and_b32_e32 v47, 0xffff0000, v173
	v_pk_add_f32 v[44:45], v[48:49], v[44:45]
	v_lshl_add_u64 v[48:49], s[78:79], 0, v[52:53]
	v_pk_add_f32 v[46:47], v[50:51], v[46:47]
	v_lshl_add_u64 v[48:49], v[48:49], 0, v[144:145]
	global_store_dwordx4 v[48:49], v[44:47], off sc1
	s_nop 1
	v_lshlrev_b32_e32 v44, 16, v170
	v_and_b32_e32 v45, 0xffff0000, v170
	v_lshlrev_b32_e32 v46, 16, v171
	v_and_b32_e32 v47, 0xffff0000, v171
	v_pk_add_f32 v[42:43], v[42:43], v[46:47]
	v_pk_add_f32 v[40:41], v[40:41], v[44:45]
	global_store_dwordx4 v[48:49], v[40:43], off offset:64 sc1
	s_nop 1
	v_lshlrev_b32_e32 v40, 16, v166
	v_and_b32_e32 v41, 0xffff0000, v166
	v_lshlrev_b32_e32 v42, 16, v167
	v_and_b32_e32 v43, 0xffff0000, v167
	v_pk_add_f32 v[38:39], v[38:39], v[42:43]
	v_pk_add_f32 v[36:37], v[36:37], v[40:41]
	global_store_dwordx4 v[48:49], v[36:39], off offset:512 sc1
	s_nop 1
	v_lshlrev_b32_e32 v36, 16, v164
	v_and_b32_e32 v37, 0xffff0000, v164
	v_lshlrev_b32_e32 v38, 16, v165
	v_and_b32_e32 v39, 0xffff0000, v165
	v_pk_add_f32 v[30:31], v[30:31], v[38:39]
	v_pk_add_f32 v[28:29], v[28:29], v[36:37]
	global_store_dwordx4 v[48:49], v[28:31], off offset:576 sc1
	v_lshlrev_b64 v[36:37], 12, v[150:151]
	s_nop 0
	v_lshlrev_b32_e32 v28, 16, v162
	v_and_b32_e32 v29, 0xffff0000, v162
	v_lshlrev_b32_e32 v30, 16, v163
	v_and_b32_e32 v31, 0xffff0000, v163
	v_pk_add_f32 v[28:29], v[32:33], v[28:29]
	v_lshl_add_u64 v[32:33], s[78:79], 0, v[36:37]
	v_pk_add_f32 v[30:31], v[34:35], v[30:31]
	v_lshl_add_u64 v[32:33], v[32:33], 0, v[144:145]
	global_store_dwordx4 v[32:33], v[28:31], off sc1
	s_nop 1
	v_lshlrev_b32_e32 v28, 16, v158
	v_and_b32_e32 v29, 0xffff0000, v158
	v_lshlrev_b32_e32 v30, 16, v159
	v_and_b32_e32 v31, 0xffff0000, v159
	v_pk_add_f32 v[26:27], v[26:27], v[30:31]
	v_pk_add_f32 v[24:25], v[24:25], v[28:29]
	global_store_dwordx4 v[32:33], v[24:27], off offset:64 sc1
	s_nop 1
	v_lshlrev_b32_e32 v24, 16, v156
	v_and_b32_e32 v25, 0xffff0000, v156
	v_lshlrev_b32_e32 v26, 16, v157
	v_and_b32_e32 v27, 0xffff0000, v157
	v_pk_add_f32 v[22:23], v[22:23], v[26:27]
	v_pk_add_f32 v[20:21], v[20:21], v[24:25]
	global_store_dwordx4 v[32:33], v[20:23], off offset:512 sc1
	s_nop 1
	v_lshlrev_b32_e32 v20, 16, v154
	v_and_b32_e32 v21, 0xffff0000, v154
	v_lshlrev_b32_e32 v22, 16, v155
	v_and_b32_e32 v23, 0xffff0000, v155
	v_pk_add_f32 v[14:15], v[14:15], v[22:23]
	v_pk_add_f32 v[12:13], v[12:13], v[20:21]
	global_store_dwordx4 v[32:33], v[12:15], off offset:576 sc1
	v_lshlrev_b64 v[20:21], 12, v[140:141]
	s_nop 0
	v_lshlrev_b32_e32 v12, 16, v152
	v_and_b32_e32 v13, 0xffff0000, v152
	v_lshlrev_b32_e32 v14, 16, v153
	v_and_b32_e32 v15, 0xffff0000, v153
	v_pk_add_f32 v[12:13], v[16:17], v[12:13]
	v_lshl_add_u64 v[16:17], s[78:79], 0, v[20:21]
	v_pk_add_f32 v[14:15], v[18:19], v[14:15]
	v_lshl_add_u64 v[16:17], v[16:17], 0, v[144:145]
	global_store_dwordx4 v[16:17], v[12:15], off sc1
	s_nop 1
	v_lshlrev_b32_e32 v12, 16, v148
	v_and_b32_e32 v13, 0xffff0000, v148
	v_lshlrev_b32_e32 v14, 16, v149
	v_and_b32_e32 v15, 0xffff0000, v149
	v_pk_add_f32 v[10:11], v[10:11], v[14:15]
	v_pk_add_f32 v[8:9], v[8:9], v[12:13]
	global_store_dwordx4 v[16:17], v[8:11], off offset:64 sc1
	s_nop 1
	v_lshlrev_b32_e32 v8, 16, v146
	v_and_b32_e32 v9, 0xffff0000, v146
	v_lshlrev_b32_e32 v10, 16, v147
	v_and_b32_e32 v11, 0xffff0000, v147
	v_pk_add_f32 v[6:7], v[6:7], v[10:11]
	v_pk_add_f32 v[4:5], v[4:5], v[8:9]
	global_store_dwordx4 v[16:17], v[4:7], off offset:512 sc1
	s_nop 1
	v_lshlrev_b32_e32 v4, 16, v142
	v_and_b32_e32 v5, 0xffff0000, v142
	v_lshlrev_b32_e32 v6, 16, v143
	v_and_b32_e32 v7, 0xffff0000, v143
	v_pk_add_f32 v[2:3], v[2:3], v[6:7]
	v_pk_add_f32 v[0:1], v[0:1], v[4:5]
	global_store_dwordx4 v[16:17], v[0:3], off offset:576 sc1
	s_cbranch_vccz .LBB0_671
	s_waitcnt vmcnt(0)
	s_cmpk_gt_u32 s28, 0xff
	s_cbranch_scc1 .LBB0_682
	s_barrier
